# work-queue item slot double-buffered in LDS, one barrier per fetch instead of two
# baseline (speedup 1.0000x reference)
.LBB0_315:
	v_mov_b32_e32 v0, v172
	v_xor_b32_e32 v254, 0x80000000, v254
	s_nop 0
	v_cmp_eq_u32_e32 vcc, 0, v0
	s_and_saveexec_b64 s[0:1], vcc
	s_cbranch_execz .LBB0_319
	s_add_u32 s98, s8, 4
	v_cmp_eq_u32_e32 vcc, s98, v253
	s_nop 4
	s_cbranch_vccnz .Lqf_dyn_1
	v_mov_b32_e32 v253, s98
	v_and_b32_e32 v0, 0x7fffffff, v254
	s_branch .Lqf_wr_1

.Lqf_wr_1:
	v_lshrrev_b32_e32 v252, 29, v254
	v_and_b32_e32 v252, 4, v252
	v_add_u32_e32 v252, v176, v252
	ds_write_b32 v252, v0
.LBB0_319:
	s_or_b64 exec, exec, s[0:1]
	s_waitcnt lgkmcnt(0)
	s_barrier
	v_lshrrev_b32_e32 v0, 29, v254
	v_and_b32_e32 v0, 4, v0
	v_add_u32_e32 v0, v176, v0
	ds_read_b32 v0, v0
	s_movk_i32 s0, 0x8ff
	s_waitcnt lgkmcnt(0)
	v_cmp_lt_i32_e32 vcc, s0, v0
	v_readfirstlane_b32 s16, v0
	s_mov_b64 s[0:1], -1
	s_cbranch_vccnz .LBB0_314
	s_cmpk_gt_i32 s16, 0x2ff
	s_cbranch_scc0 .LBB0_379
	s_cmpk_gt_u32 s16, 0x5ff
	s_cbranch_scc0 .LBB0_366
	s_add_i32 s0, s16, 0xfffffa00
	s_lshr_b32 s1, s0, 2
	s_sub_i32 s2, s1, 64
	s_lshr_b32 s2, s2, 6
	s_and_b32 s18, s16, 3
	s_add_i32 s2, s2, 16
	s_lshr_b32 s3, s0, 4
	s_cmpk_lt_u32 s0, 0x100
	s_cselect_b32 s0, 3, 63
	s_cselect_b32 s19, s3, s2
	s_and_b32 s17, s0, s1
	s_cmp_lt_u32 s19, 16
	v_mov_b32_e32 v1, v172
	s_cselect_b64 s[0:1], -1, 0
	s_cmp_gt_u32 s19, 15
	s_movk_i32 s2, 0x80
	s_cselect_b64 s[4:5], -1, 0
	v_ashrrev_i32_e32 v6, 6, v1
	v_and_b32_e32 v0, 63, v1
	v_cmp_gt_i32_e32 vcc, s2, v1
	s_barrier
	s_and_saveexec_b64 s[12:13], vcc
	s_cbranch_execz .LBB0_357
	v_lshl_or_b32 v3, s17, 6, v0
	s_mov_b64 s[2:3], -1
	s_and_b64 vcc, exec, s[4:5]
	s_cbranch_vccz .LBB0_325
	v_lshl_or_b32 v2, v0, 6, s17
	s_lshl_b32 s2, s19, 12
	v_cndmask_b32_e64 v2, v2, v3, s[36:37]
	s_add_i32 s2, s2, 0xffff1000
	v_or_b32_e32 v2, s2, v2
	s_mov_b64 s[2:3], 0

.LBB0_462:
	v_mov_b32_e32 v0, v172
	v_xor_b32_e32 v254, 0x80000000, v254
	s_nop 0
	v_cmp_eq_u32_e32 vcc, 0, v0
	s_and_saveexec_b64 s[0:1], vcc
	s_cbranch_execz .LBB0_466
	s_add_u32 s98, s6, 8
	v_cmp_eq_u32_e32 vcc, s98, v253
	s_nop 4
	s_cbranch_vccnz .Lqf_dyn_2
	v_mov_b32_e32 v253, s98
	v_and_b32_e32 v0, 0x7fffffff, v254
	s_branch .Lqf_wr_2

.LBB0_466:
	s_or_b64 exec, exec, s[0:1]
	s_waitcnt lgkmcnt(0)
	s_barrier
	v_lshrrev_b32_e32 v0, 29, v254
	v_and_b32_e32 v0, 4, v0
	v_add_u32_e32 v0, v176, v0
	ds_read_b32 v0, v0
	s_movk_i32 s0, 0x47f
	s_waitcnt lgkmcnt(0)
	v_cmp_lt_i32_e32 vcc, s0, v0
	v_readfirstlane_b32 s14, v0
	s_mov_b64 s[0:1], -1
	s_cbranch_vccnz .LBB0_461
	s_cmpk_gt_i32 s14, 0x17f
	s_cbranch_scc0 .LBB0_508
	s_add_i32 s0, s14, 0xfffffe80
	s_lshr_b32 s1, s0, 2
	s_sub_i32 s2, s1, 64
	s_lshr_b32 s2, s2, 6
	s_and_b32 s16, s14, 3
	s_add_i32 s2, s2, 16
	s_lshr_b32 s3, s0, 4
	s_cmpk_lt_u32 s0, 0x100
	s_cselect_b32 s0, 3, 63
	s_cselect_b32 s17, s3, s2
	s_and_b32 s15, s0, s1
	s_cmp_lt_u32 s17, 16
	v_mov_b32_e32 v1, v172
	s_cselect_b64 s[8:9], -1, 0
	s_cmp_gt_u32 s17, 15
	s_movk_i32 s0, 0x80
	s_cselect_b64 s[2:3], -1, 0
	v_ashrrev_i32_e32 v4, 6, v1
	v_and_b32_e32 v0, 63, v1
	v_cmp_gt_i32_e32 vcc, s0, v1
	s_barrier
	s_and_saveexec_b64 s[10:11], vcc
	s_cbranch_execz .LBB0_500
	v_lshl_or_b32 v3, s15, 6, v0
	s_mov_b64 s[0:1], -1
	s_and_b64 vcc, exec, s[2:3]
	s_cbranch_vccnz .LBB0_525
	s_andn2_b64 vcc, exec, s[0:1]
	s_cbranch_vccz .LBB0_526

.LBB0_578:
	v_xor_b32_e32 v254, 0x80000000, v254
	s_and_saveexec_b64 s[0:1], s[36:37]
	s_cbranch_execz .LBB0_582
	s_add_u32 s98, s20, 0
	v_cmp_eq_u32_e32 vcc, s98, v253
	s_nop 4
	s_cbranch_vccnz .Lqf_dyn_3
	v_mov_b32_e32 v253, s98
	v_and_b32_e32 v0, 0x7fffffff, v254
	s_branch .Lqf_wr_3

.LBB0_582:
	s_or_b64 exec, exec, s[0:1]
	s_waitcnt lgkmcnt(0)
	s_barrier
	v_lshrrev_b32_e32 v0, 29, v254
	v_and_b32_e32 v0, 4, v0
	v_add_u32_e32 v0, v176, v0
	ds_read_b32 v0, v0
	s_movk_i32 s0, 0x483
	s_waitcnt lgkmcnt(0)
	v_cmp_lt_i32_e32 vcc, s0, v0
	v_readfirstlane_b32 s51, v0
	s_mov_b64 s[0:1], -1
	s_cbranch_vccnz .LBB0_577
	s_cmpk_gt_i32 s51, 0x1df
	s_cbranch_scc0 .LBB0_696
	s_cmpk_gt_u32 s51, 0x263
	s_mov_b32 s63, 0x800000
	s_cbranch_scc0 .LBB0_632
	s_cmpk_gt_u32 s51, 0x363
	s_cbranch_scc0 .LBB0_623
	s_add_i32 s62, s51, 0xfffffc9c
	s_cmpk_gt_u32 s51, 0x3e3
	s_cbranch_scc0 .LBB0_620
	s_cmpk_gt_u32 s51, 0x463
	s_cbranch_scc0 .LBB0_589
	s_lshl_b32 s2, s51, 1
	s_and_b32 s2, s2, 0x7ffffffc
	s_and_b32 s0, s51, 1
	s_addk_i32 s2, 0xf738
	s_lshl_b32 s1, s0, 8
	s_lshl_b32 s3, s2, 9
	v_mov_b32_e32 v0, v172
	s_or_b32 s1, s3, s1
	v_readlane_b32 s4, v247, 8
	v_add_u32_e32 v2, s1, v0
	v_ashrrev_i32_e32 v3, 31, v2
	v_lshlrev_b64 v[4:5], 2, v[2:3]
	v_readlane_b32 s5, v247, 9
	v_readlane_b32 s6, v247, 10
	v_readlane_b32 s7, v247, 11
	v_lshl_add_u64 v[6:7], s[4:5], 0, v[4:5]
	global_load_dword v1, v[6:7], off
	v_lshl_add_u64 v[6:7], s[6:7], 0, v[4:5]
	global_load_dword v12, v[6:7], off
	v_add_u32_e32 v6, 0x200, v2
	v_ashrrev_i32_e32 v7, 31, v6
	v_lshlrev_b64 v[6:7], 2, v[6:7]
	s_waitcnt vmcnt(7)
	v_lshl_add_u64 v[8:9], s[4:5], 0, v[6:7]
	global_load_dword v13, v[8:9], off
	v_lshl_add_u64 v[8:9], s[6:7], 0, v[6:7]
	global_load_dword v14, v[8:9], off
	v_add_u32_e32 v8, 0x400, v2
	v_ashrrev_i32_e32 v9, 31, v8
	v_lshlrev_b64 v[8:9], 2, v[8:9]
	v_add_u32_e32 v2, 0x600, v2
	v_lshl_add_u64 v[10:11], s[4:5], 0, v[8:9]
	v_ashrrev_i32_e32 v3, 31, v2
	global_load_dword v15, v[10:11], off
	v_lshl_add_u64 v[10:11], s[6:7], 0, v[8:9]
	v_lshlrev_b64 v[2:3], 2, v[2:3]
	global_load_dword v16, v[10:11], off
	v_lshl_add_u64 v[10:11], s[4:5], 0, v[2:3]
	global_load_dword v17, v[10:11], off
	v_lshl_add_u64 v[10:11], s[6:7], 0, v[2:3]
	global_load_dword v10, v[10:11], off
	s_add_i32 s2, s2, s44
	s_or_b32 s0, s2, s0
	s_lshl_b32 s0, s0, 8
	s_ashr_i32 s1, s0, 31
	s_lshl_b64 s[0:1], s[0:1], 2
	v_readlane_b32 s4, v247, 12
	s_add_u32 s0, s80, s0
	v_readlane_b32 s5, v247, 13
	s_addc_u32 s1, s81, s1
	s_waitcnt vmcnt(6)
	v_fmac_f32_e32 v12, 0, v1
	v_ashrrev_i32_e32 v1, 31, v0
	v_lshl_add_u64 v[4:5], s[4:5], 0, v[4:5]
	v_lshl_add_u64 v[0:1], v[0:1], 2, s[0:1]
	global_store_dword v[4:5], v149, off
	v_lshl_add_u64 v[4:5], s[4:5], 0, v[6:7]
	v_add_co_u32_e32 v0, vcc, 0x3c10000, v0
	s_waitcnt vmcnt(5)
	v_fmac_f32_e32 v14, v12, v13
	global_store_dword v[4:5], v12, off
	v_lshl_add_u64 v[4:5], s[4:5], 0, v[8:9]
	v_lshl_add_u64 v[2:3], s[4:5], 0, v[2:3]
	v_addc_co_u32_e32 v1, vcc, 0, v1, vcc
	global_store_dword v[4:5], v14, off
	s_mov_b64 s[0:1], 0
	s_waitcnt vmcnt(5)
	v_fmac_f32_e32 v16, v14, v15
	global_store_dword v[2:3], v16, off
	s_waitcnt vmcnt(4)
	v_fmac_f32_e32 v10, v16, v17
	global_store_dword v[0:1], v10, off offset:1024

.LBB0_805:
	v_mov_b32_e32 v0, v172
	s_waitcnt lgkmcnt(0)
	v_xor_b32_e32 v254, 0x80000000, v254
	s_nop 0
	v_cmp_eq_u32_e32 vcc, 0, v0
	s_and_saveexec_b64 s[0:1], vcc
	s_cbranch_execz .LBB0_809
	s_add_u32 s98, s26, 12
	v_cmp_eq_u32_e32 vcc, s98, v253
	s_nop 4
	s_cbranch_vccnz .Lqf_dyn_4
	v_mov_b32_e32 v253, s98
	v_and_b32_e32 v0, 0x7fffffff, v254
	v_add_u32_e32 v0, -16, v0
	s_branch .Lqf_wr_4

.LBB0_809:
	s_or_b64 exec, exec, s[0:1]
	s_waitcnt lgkmcnt(0)
	s_barrier
	v_lshrrev_b32_e32 v0, 29, v254
	v_and_b32_e32 v0, 4, v0
	v_add_u32_e32 v0, v176, v0
	ds_read_b32 v0, v0
	s_movk_i32 s0, 0x6bf
	s_waitcnt lgkmcnt(0)
	v_cmp_lt_i32_e32 vcc, s0, v0
	v_readfirstlane_b32 s28, v0
	s_mov_b64 s[0:1], -1
	s_cbranch_vccnz .LBB0_804
	s_cmp_gt_i32 s28, -1
	s_cbranch_scc0 .LBB0_1058
	s_cmpk_gt_u32 s28, 0xbf
	s_cbranch_scc0 .LBB0_964
	s_and_b32 s18, s28, 3
	s_cmpk_gt_u32 s28, 0x3bf
	s_cbranch_scc0 .LBB0_865
	s_add_i32 s0, s28, 0xfffffc40
	s_lshr_b32 s1, s0, 2
	s_sub_i32 s2, 0xbf, s1
	s_sub_i32 s1, 0x7f, s1
	s_lshr_b32 s1, s1, 6
	s_add_i32 s1, s1, 16
	s_lshr_b32 s3, s2, 2
	s_cmpk_gt_u32 s0, 0x1ff
	s_cselect_b32 s0, 3, 63
	s_cselect_b32 s12, s3, s1
	s_and_b32 s11, s0, s2
	s_cmp_lt_u32 s12, 16
	s_cselect_b64 s[2:3], -1, 0
	s_cmp_gt_u32 s12, 15
	v_mov_b32_e32 v28, v172
	s_cselect_b64 s[6:7], -1, 0
	s_nop 0
	v_cmp_gt_i32_e32 vcc, 64, v28
	s_barrier
	s_and_saveexec_b64 s[0:1], vcc
	s_cbranch_execz .LBB0_819
	v_lshl_add_u32 v0, s11, 6, v28
	s_mov_b64 s[4:5], -1
	s_and_b64 vcc, exec, s[6:7]
	s_cbranch_vccz .LBB0_816
	v_lshlrev_b32_e32 v1, 6, v28
	v_and_b32_e32 v1, 0xfc0, v1
	v_ashrrev_i32_e32 v2, 6, v0
	v_readlane_b32 s6, v249, 20
	s_lshl_b32 s4, s12, 12
	v_add_u32_e32 v1, v1, v2
	v_readlane_b32 s7, v249, 21
	s_add_i32 s4, s4, 0xffff1000
	s_nop 0
	v_cndmask_b32_e64 v1, v1, v0, s[6:7]
	v_add_u32_e32 v1, s4, v1
	s_mov_b64 s[4:5], 0
